# FFN conv+GeGLU phase: per-row load->wait chain replaced by 4-row prefetch ring with counted vmcnt
# speedup vs baseline: 1.0258x; 1.0258x over previous
.LBB0_560:
	s_and_b64 s[8:9], s[12:13], exec
	s_cselect_b32 s14, 32, 8
	s_waitcnt vmcnt(14)
	v_mov_b32_e32 v122, v90
	s_waitcnt vmcnt(12)
	v_mov_b32_e32 v123, v6
	s_waitcnt vmcnt(2)
	v_mov_b32_e32 v124, v94
	s_waitcnt vmcnt(0)
	v_mov_b32_e32 v125, v30
	v_mov_b32_e32 v126, v82
	v_mov_b32_e32 v127, v14
	v_mov_b32_e32 v128, v86
	v_mov_b32_e32 v129, v22
	v_mov_b32_e32 v6, v91
	v_mov_b32_e32 v30, v95
	v_mov_b32_e32 v14, v83
	v_mov_b32_e32 v22, v87
	v_mov_b32_e32 v82, v92
	v_mov_b32_e32 v83, v8
	v_mov_b32_e32 v86, v96
	v_mov_b32_e32 v87, v32
	v_mov_b32_e32 v90, v84
	v_mov_b32_e32 v91, v16
	v_mov_b32_e32 v94, v88
	v_mov_b32_e32 v95, v24
	v_mov_b32_e32 v8, v93
	v_mov_b32_e32 v32, v97
	v_mov_b32_e32 v16, v85
	v_mov_b32_e32 v24, v89
	v_mov_b32_e32 v84, v74
	v_mov_b32_e32 v85, v2
	v_mov_b32_e32 v88, v78
	v_mov_b32_e32 v89, v26
	v_mov_b32_e32 v92, v66
	v_mov_b32_e32 v93, v10
	v_mov_b32_e32 v96, v70
	v_mov_b32_e32 v97, v18
	v_mov_b32_e32 v2, v75
	v_mov_b32_e32 v26, v79
	v_mov_b32_e32 v10, v67
	v_mov_b32_e32 v18, v71
	v_mov_b32_e32 v66, v76
	v_mov_b32_e32 v67, v4
	v_mov_b32_e32 v70, v80
	v_mov_b32_e32 v71, v28
	v_mov_b32_e32 v74, v68
	v_mov_b32_e32 v75, v12
	v_mov_b32_e32 v78, v72
	v_mov_b32_e32 v79, v20
	v_mov_b32_e32 v4, v77
	v_mov_b32_e32 v28, v81
	v_mov_b32_e32 v12, v69
	v_mov_b32_e32 v20, v73
	v_mad_i64_i32 v[68:69], s[8:9], s19, v213, v[106:107]
	v_mad_i64_i32 v[72:73], s[8:9], s19, v214, v[120:121]
	s_mov_b32 s15, 0
	s_mov_b64 s[22:23], 0x2c00
	v_mov_b32_e32 v232, v72
	v_mov_b32_e32 v233, v73
	v_add_co_u32_e32 v234, vcc, v213, v72
	v_addc_co_u32_e32 v235, vcc, 0, v73, vcc
	global_load_dwordx4 v[172:175], v[232:233], off
	global_load_dwordx4 v[176:179], v[234:235], off
	global_load_dwordx4 v[236:239], v[72:73], off
	v_lshl_add_u64 v[232:233], v[232:233], 0, s[22:23]
	v_lshl_add_u64 v[234:235], v[234:235], 0, s[22:23]
	global_load_dwordx4 v[180:183], v[232:233], off
	global_load_dwordx4 v[184:187], v[234:235], off
	global_load_dwordx4 v[236:239], v[72:73], off
	v_lshl_add_u64 v[232:233], v[232:233], 0, s[22:23]
	v_lshl_add_u64 v[234:235], v[234:235], 0, s[22:23]
	global_load_dwordx4 v[188:191], v[232:233], off
	global_load_dwordx4 v[220:223], v[234:235], off
	global_load_dwordx4 v[236:239], v[72:73], off
	v_lshl_add_u64 v[232:233], v[232:233], 0, s[22:23]
	v_lshl_add_u64 v[234:235], v[234:235], 0, s[22:23]
	global_load_dwordx4 v[224:227], v[232:233], off
	global_load_dwordx4 v[228:231], v[234:235], off
	global_load_dwordx4 v[236:239], v[72:73], off
	v_lshl_add_u64 v[232:233], v[232:233], 0, s[22:23]
	v_lshl_add_u64 v[234:235], v[234:235], 0, s[22:23]
.LBB0_561:
	v_add_co_u32_e32 v76, vcc, s33, v72
	s_add_i32 s13, s19, s15
	s_nop 0
	v_addc_co_u32_e32 v77, vcc, 0, v73, vcc
	s_mul_i32 s12, s13, 0x2c00
	s_add_i32 s16, s13, 1
	s_add_i32 s8, s12, 0x2c00
	s_mul_hi_i32 s9, s16, 0x2c00
	s_add_u32 s8, s80, s8
	s_addc_u32 s9, s81, s9
	s_waitcnt vmcnt(10)
	v_and_b32_e32 v138, 0xffff0000, v172
	v_lshlrev_b32_e32 v140, 16, v172
	v_and_b32_e32 v134, 0xffff0000, v173
	v_lshlrev_b32_e32 v136, 16, v173
	v_mov_b32_e32 v142, v54
	v_mov_b32_e32 v143, v58
	v_mov_b32_e32 v58, v55
	v_and_b32_e32 v130, 0xffff0000, v174
	v_lshlrev_b32_e32 v132, 16, v174
	v_and_b32_e32 v76, 0xffff0000, v175
	v_lshlrev_b32_e32 v80, 16, v175
	v_pk_fma_f32 v[144:145], v[122:123], v[142:143], v[124:125]
	v_mov_b32_e32 v143, v46
	v_pk_fma_f32 v[54:55], v[6:7], v[58:59], v[30:31]
	v_mov_b32_e32 v46, v63
	s_waitcnt vmcnt(10)
	v_and_b32_e32 v139, 0xffff0000, v176
	v_pk_fma_f32 v[54:55], v[14:15], v[46:47], v[54:55]
	v_mov_b32_e32 v142, v62
	v_pk_fma_f32 v[54:55], v[22:23], v[138:139], v[54:55]
	v_lshlrev_b32_e32 v137, 16, v177
	v_mul_f32_e32 v58, 0x3d372713, v55
	v_mul_f32_e32 v58, v55, v58
	v_fma_f32 v58, v55, v58, v55
	v_mul_f32_e32 v58, 0x3f4c422a, v58
	v_mul_f32_e32 v58, -2.0, v58
	v_mul_f32_e32 v58, 0x3fb8aa3b, v58
	v_exp_f32_e32 v58, v58
	v_and_b32_e32 v135, 0xffff0000, v177
	v_lshlrev_b32_e32 v133, 16, v178
	v_and_b32_e32 v131, 0xffff0000, v178
	v_add_f32_e32 v58, 1.0, v58
	v_rcp_f32_e32 v58, v58
	v_lshlrev_b32_e32 v81, 16, v179
	v_and_b32_e32 v77, 0xffff0000, v179
	v_lshlrev_b32_e32 v141, 16, v176
	global_load_dwordx4 v[172:175], v[232:233], off
	global_load_dwordx4 v[176:179], v[234:235], off
	v_lshl_add_u64 v[232:233], v[232:233], 0, s[22:23]
	v_lshl_add_u64 v[234:235], v[234:235], 0, s[22:23]
	v_mul_f32_e32 v55, v55, v58
	v_mul_f32_e32 v62, v54, v55
	v_mov_b32_e32 v54, v56
	v_mov_b32_e32 v55, v60
	v_pk_fma_f32 v[58:59], v[82:83], v[54:55], v[86:87]
	v_mov_b32_e32 v54, v64
	v_mov_b32_e32 v55, v48
	v_pk_fma_f32 v[58:59], v[90:91], v[54:55], v[58:59]
	v_mov_b32_e32 v60, v57
	v_pk_fma_f32 v[58:59], v[94:95], v[136:137], v[58:59]
	v_pk_fma_f32 v[56:57], v[8:9], v[60:61], v[32:33]
	v_mul_f32_e32 v48, 0x3d372713, v59
	v_mul_f32_e32 v48, v59, v48
	v_fma_f32 v48, v59, v48, v59
	v_mul_f32_e32 v48, 0x3f4c422a, v48
	v_mul_f32_e32 v48, -2.0, v48
	v_mul_f32_e32 v48, 0x3fb8aa3b, v48
	v_exp_f32_e32 v48, v48
	v_pk_fma_f32 v[144:145], v[126:127], v[142:143], v[144:145]
	v_add_f32_e32 v48, 1.0, v48
	v_rcp_f32_e32 v48, v48
	v_pk_fma_f32 v[144:145], v[128:129], v[140:141], v[144:145]
	v_mul_f32_e32 v48, v59, v48
	v_mul_f32_e32 v63, v58, v48
	v_mov_b32_e32 v48, v65
	v_pk_fma_f32 v[56:57], v[16:17], v[48:49], v[56:57]
	v_mul_f32_e32 v0, 0x3d372713, v145
	v_pk_fma_f32 v[56:57], v[24:25], v[134:135], v[56:57]
	v_mul_f32_e32 v0, v145, v0
	v_mul_f32_e32 v58, 0x3d372713, v57
	v_mul_f32_e32 v58, v57, v58
	v_fma_f32 v58, v57, v58, v57
	v_mul_f32_e32 v58, 0x3f4c422a, v58
	v_mul_f32_e32 v58, -2.0, v58
	v_mul_f32_e32 v58, 0x3fb8aa3b, v58
	v_exp_f32_e32 v58, v58
	v_fma_f32 v0, v145, v0, v145
	v_mul_f32_e32 v0, 0x3f4c422a, v0
	v_mul_f32_e32 v0, -2.0, v0
	v_add_f32_e32 v58, 1.0, v58
	v_rcp_f32_e32 v58, v58
	v_mul_f32_e32 v0, 0x3fb8aa3b, v0
	v_exp_f32_e32 v0, v0
	v_mul_f32_e32 v57, v57, v58
	v_mul_f32_e32 v60, v56, v57
	v_mov_b32_e32 v56, v34
	v_mov_b32_e32 v57, v42
	v_pk_fma_f32 v[58:59], v[84:85], v[56:57], v[88:89]
	v_mov_b32_e32 v56, v50
	v_mov_b32_e32 v57, v38
	v_pk_fma_f32 v[58:59], v[92:93], v[56:57], v[58:59]
	v_mov_b32_e32 v42, v35
	v_pk_fma_f32 v[58:59], v[96:97], v[132:133], v[58:59]
	v_mov_b32_e32 v38, v51
	v_mul_f32_e32 v34, 0x3d372713, v59
	v_mul_f32_e32 v34, v59, v34
	v_fma_f32 v34, v59, v34, v59
	v_mul_f32_e32 v34, 0x3f4c422a, v34
	v_mul_f32_e32 v34, -2.0, v34
	v_mul_f32_e32 v34, 0x3fb8aa3b, v34
	v_exp_f32_e32 v34, v34
	v_add_f32_e32 v0, 1.0, v0
	v_rcp_f32_e32 v0, v0
	v_add_f32_e32 v34, 1.0, v34
	v_rcp_f32_e32 v34, v34
	v_mul_f32_e32 v0, v145, v0
	v_mul_f32_e32 v0, v144, v0
	v_mul_f32_e32 v34, v59, v34
	v_mul_f32_e32 v50, v58, v34
	v_pk_fma_f32 v[34:35], v[2:3], v[42:43], v[26:27]
	s_nop 0
	v_pk_fma_f32 v[34:35], v[10:11], v[38:39], v[34:35]
	s_nop 0
	v_pk_fma_f32 v[34:35], v[18:19], v[130:131], v[34:35]
	s_nop 0
	v_mul_f32_e32 v42, 0x3d372713, v35
	v_mul_f32_e32 v42, v35, v42
	v_fma_f32 v42, v35, v42, v35
	v_mul_f32_e32 v42, 0x3f4c422a, v42
	v_mul_f32_e32 v42, -2.0, v42
	v_mul_f32_e32 v42, 0x3fb8aa3b, v42
	v_exp_f32_e32 v42, v42
	s_nop 0
	v_add_f32_e32 v42, 1.0, v42
	v_rcp_f32_e32 v42, v42
	s_nop 0
	v_mul_f32_e32 v35, v35, v42
	v_mul_f32_e32 v51, v34, v35
	v_mov_b32_e32 v34, v36
	v_mov_b32_e32 v35, v44
	v_pk_fma_f32 v[42:43], v[66:67], v[34:35], v[70:71]
	v_mov_b32_e32 v34, v52
	v_mov_b32_e32 v35, v40
	v_pk_fma_f32 v[42:43], v[74:75], v[34:35], v[42:43]
	v_mov_b32_e32 v44, v37
	v_pk_fma_f32 v[42:43], v[78:79], v[80:81], v[42:43]
	v_mov_b32_e32 v40, v53
	v_mul_f32_e32 v36, 0x3d372713, v43
	v_mul_f32_e32 v36, v43, v36
	v_fma_f32 v36, v43, v36, v43
	v_mul_f32_e32 v36, 0x3f4c422a, v36
	v_mul_f32_e32 v36, -2.0, v36
	v_mul_f32_e32 v36, 0x3fb8aa3b, v36
	v_exp_f32_e32 v36, v36
	v_pk_fma_f32 v[34:35], v[66:67], v[34:35], v[70:71]
	v_add_f32_e32 v36, 1.0, v36
	v_rcp_f32_e32 v36, v36
	v_pk_fma_f32 v[34:35], v[74:75], v[80:81], v[34:35]
	v_mul_f32_e32 v36, v43, v36
	v_mul_f32_e32 v52, v42, v36
	v_pk_fma_f32 v[36:37], v[4:5], v[44:45], v[28:29]
	v_cvt_pk_bf16_f32 v43, v63, v60
	v_cvt_pk_bf16_f32 v44, v50, v51
	s_nop 0
	v_pk_fma_f32 v[36:37], v[12:13], v[40:41], v[36:37]
	s_nop 0
	v_pk_fma_f32 v[36:37], v[20:21], v[76:77], v[36:37]
	s_nop 0
	v_mul_f32_e32 v42, 0x3d372713, v37
	v_mul_f32_e32 v42, v37, v42
	v_fma_f32 v42, v37, v42, v37
	v_mul_f32_e32 v42, 0x3f4c422a, v42
	v_mul_f32_e32 v42, -2.0, v42
	v_mul_f32_e32 v42, 0x3fb8aa3b, v42
	v_exp_f32_e32 v42, v42
	s_nop 0
	v_add_f32_e32 v42, 1.0, v42
	v_rcp_f32_e32 v42, v42
	s_nop 0
	v_mul_f32_e32 v37, v37, v42
	v_mul_f32_e32 v36, v36, v37
	v_cvt_pk_bf16_f32 v42, v0, v62
	v_cvt_pk_bf16_f32 v45, v52, v36
	global_store_dwordx4 v[68:69], v[42:45], off
	v_lshl_add_u64 v[36:37], s[8:9], 0, v[104:105]
	v_add_co_u32_e32 v36, vcc, s33, v36
	v_lshl_add_u64 v[68:69], v[68:69], 0, s[44:45]
	s_nop 0
	v_addc_co_u32_e32 v37, vcc, 0, v37, vcc
	v_pk_fma_f32 v[36:37], v[122:123], v[142:143], v[124:125]
	s_waitcnt vmcnt(10)
	v_lshlrev_b32_e32 v170, 16, v180
	v_pk_fma_f32 v[36:37], v[126:127], v[140:141], v[36:37]
	v_and_b32_e32 v164, 0xffff0000, v180
	v_and_b32_e32 v58, 0xffff0000, v182
	v_lshlrev_b32_e32 v62, 16, v182
	v_lshlrev_b32_e32 v150, 16, v181
	s_waitcnt vmcnt(10)
	v_lshlrev_b32_e32 v171, 16, v184
	v_pk_fma_f32 v[36:37], v[128:129], v[170:171], v[36:37]
	v_and_b32_e32 v165, 0xffff0000, v184
	v_mul_f32_e32 v0, 0x3d372713, v37
	v_mul_f32_e32 v0, v37, v0
	v_fma_f32 v0, v37, v0, v37
	v_mul_f32_e32 v0, 0x3f4c422a, v0
	v_mul_f32_e32 v0, -2.0, v0
	v_mul_f32_e32 v0, 0x3fb8aa3b, v0
	v_exp_f32_e32 v0, v0
	v_lshlrev_b32_e32 v151, 16, v185
	v_and_b32_e32 v42, 0xffff0000, v183
	v_lshlrev_b32_e32 v50, 16, v183
	v_add_f32_e32 v0, 1.0, v0
	v_rcp_f32_e32 v0, v0
	v_and_b32_e32 v144, 0xffff0000, v181
	v_and_b32_e32 v145, 0xffff0000, v185
	v_lshlrev_b32_e32 v63, 16, v186
	v_mul_f32_e32 v0, v37, v0
	v_mul_f32_e32 v0, v36, v0
	v_pk_fma_f32 v[36:37], v[6:7], v[46:47], v[30:31]
	v_and_b32_e32 v59, 0xffff0000, v186
	v_pk_fma_f32 v[36:37], v[14:15], v[138:139], v[36:37]
	v_lshlrev_b32_e32 v51, 16, v187
	v_pk_fma_f32 v[36:37], v[22:23], v[164:165], v[36:37]
	v_pk_fma_f32 v[34:35], v[78:79], v[50:51], v[34:35]
	v_mul_f32_e32 v44, 0x3d372713, v37
	v_mul_f32_e32 v44, v37, v44
	v_fma_f32 v44, v37, v44, v37
	v_mul_f32_e32 v44, 0x3f4c422a, v44
	v_mul_f32_e32 v44, -2.0, v44
	v_mul_f32_e32 v44, 0x3fb8aa3b, v44
	v_exp_f32_e32 v44, v44
	v_and_b32_e32 v43, 0xffff0000, v187
	global_load_dwordx4 v[180:183], v[232:233], off
	global_load_dwordx4 v[184:187], v[234:235], off
	v_lshl_add_u64 v[232:233], v[232:233], 0, s[22:23]
	v_lshl_add_u64 v[234:235], v[234:235], 0, s[22:23]
	v_add_f32_e32 v44, 1.0, v44
	v_rcp_f32_e32 v44, v44
	s_nop 0
	v_mul_f32_e32 v37, v37, v44
	v_mul_f32_e32 v44, v36, v37
	v_pk_fma_f32 v[36:37], v[82:83], v[54:55], v[86:87]
	s_nop 0
	v_pk_fma_f32 v[36:37], v[90:91], v[136:137], v[36:37]
	s_nop 0
	v_pk_fma_f32 v[36:37], v[94:95], v[150:151], v[36:37]
	s_nop 0
	v_mul_f32_e32 v45, 0x3d372713, v37
	v_mul_f32_e32 v45, v37, v45
	v_fma_f32 v45, v37, v45, v37
	v_mul_f32_e32 v45, 0x3f4c422a, v45
	v_mul_f32_e32 v45, -2.0, v45
	v_mul_f32_e32 v45, 0x3fb8aa3b, v45
	v_exp_f32_e32 v45, v45
	s_nop 0
	v_add_f32_e32 v45, 1.0, v45
	v_rcp_f32_e32 v45, v45
	s_nop 0
	v_mul_f32_e32 v37, v37, v45
	v_mul_f32_e32 v45, v36, v37
	v_pk_fma_f32 v[36:37], v[8:9], v[48:49], v[32:33]
	s_nop 0
	v_pk_fma_f32 v[36:37], v[16:17], v[134:135], v[36:37]
	s_nop 0
	v_pk_fma_f32 v[36:37], v[24:25], v[144:145], v[36:37]
	s_nop 0
	v_mul_f32_e32 v46, 0x3d372713, v37
	v_mul_f32_e32 v46, v37, v46
	v_fma_f32 v46, v37, v46, v37
	v_mul_f32_e32 v46, 0x3f4c422a, v46
	v_mul_f32_e32 v46, -2.0, v46
	v_mul_f32_e32 v46, 0x3fb8aa3b, v46
	v_exp_f32_e32 v46, v46
	s_nop 0
	v_add_f32_e32 v46, 1.0, v46
	v_rcp_f32_e32 v46, v46
	s_nop 0
	v_mul_f32_e32 v37, v37, v46
	v_mul_f32_e32 v46, v36, v37
	v_pk_fma_f32 v[36:37], v[84:85], v[56:57], v[88:89]
	s_nop 0
	v_pk_fma_f32 v[36:37], v[92:93], v[132:133], v[36:37]
	s_nop 0
	v_pk_fma_f32 v[36:37], v[96:97], v[62:63], v[36:37]
	s_nop 0
	v_mul_f32_e32 v47, 0x3d372713, v37
	v_mul_f32_e32 v47, v37, v47
	v_fma_f32 v47, v37, v47, v37
	v_mul_f32_e32 v47, 0x3f4c422a, v47
	v_mul_f32_e32 v47, -2.0, v47
	v_mul_f32_e32 v47, 0x3fb8aa3b, v47
	v_exp_f32_e32 v47, v47
	s_nop 0
	v_add_f32_e32 v47, 1.0, v47
	v_rcp_f32_e32 v47, v47
	s_nop 0
	v_mul_f32_e32 v37, v37, v47
	v_mul_f32_e32 v47, v36, v37
	v_pk_fma_f32 v[36:37], v[2:3], v[38:39], v[26:27]
	s_nop 0
	v_pk_fma_f32 v[36:37], v[10:11], v[130:131], v[36:37]
	s_nop 0
	v_pk_fma_f32 v[36:37], v[18:19], v[58:59], v[36:37]
	s_nop 0
	v_mul_f32_e32 v38, 0x3d372713, v37
	v_mul_f32_e32 v38, v37, v38
	v_fma_f32 v38, v37, v38, v37
	v_mul_f32_e32 v38, 0x3f4c422a, v38
	v_mul_f32_e32 v38, -2.0, v38
	v_mul_f32_e32 v38, 0x3fb8aa3b, v38
	v_exp_f32_e32 v38, v38
	s_nop 0
	v_add_f32_e32 v38, 1.0, v38
	v_rcp_f32_e32 v38, v38
	s_nop 0
	v_mul_f32_e32 v37, v37, v38
	v_mul_f32_e32 v36, v36, v37
	v_mul_f32_e32 v37, 0x3d372713, v35
	v_mul_f32_e32 v37, v35, v37
	v_fma_f32 v37, v35, v37, v35
	v_mul_f32_e32 v37, 0x3f4c422a, v37
	v_mul_f32_e32 v37, -2.0, v37
	v_mul_f32_e32 v37, 0x3fb8aa3b, v37
	v_exp_f32_e32 v37, v37
	v_cvt_pk_bf16_f32 v36, v47, v36
	s_nop 0
	v_add_f32_e32 v37, 1.0, v37
	v_rcp_f32_e32 v37, v37
	s_nop 0
	v_mul_f32_e32 v35, v35, v37
	v_mul_f32_e32 v37, v34, v35
	v_pk_fma_f32 v[34:35], v[4:5], v[40:41], v[28:29]
	s_nop 0
	v_pk_fma_f32 v[34:35], v[12:13], v[76:77], v[34:35]
	s_nop 0
	v_pk_fma_f32 v[34:35], v[20:21], v[42:43], v[34:35]
	s_nop 0
	v_mul_f32_e32 v38, 0x3d372713, v35
	v_mul_f32_e32 v38, v35, v38
	v_fma_f32 v38, v35, v38, v35
	v_mul_f32_e32 v38, 0x3f4c422a, v38
	v_mul_f32_e32 v38, -2.0, v38
	v_mul_f32_e32 v38, 0x3fb8aa3b, v38
	v_exp_f32_e32 v38, v38
	s_nop 0
	v_add_f32_e32 v38, 1.0, v38
	v_rcp_f32_e32 v38, v38
	s_nop 0
	v_mul_f32_e32 v35, v35, v38
	v_mul_f32_e32 v38, v34, v35
	v_cvt_pk_bf16_f32 v37, v37, v38
	v_mad_i64_i32 v[38:39], s[8:9], s16, v213, v[106:107]
	s_add_i32 s16, s13, 2
	s_add_i32 s8, s12, 0x5800
	s_mul_hi_i32 s9, s16, 0x2c00
	s_add_u32 s8, s80, s8
	s_addc_u32 s9, s81, s9
	v_cvt_pk_bf16_f32 v34, v0, v44
	v_cvt_pk_bf16_f32 v35, v45, v46
	global_store_dwordx4 v[38:39], v[34:37], off
	v_lshl_add_u64 v[38:39], s[8:9], 0, v[104:105]
	v_add_co_u32_e32 v38, vcc, s33, v38
	s_waitcnt vmcnt(10)
	v_and_b32_e32 v162, 0xffff0000, v188
	v_addc_co_u32_e32 v39, vcc, 0, v39, vcc
	v_lshlrev_b32_e32 v168, 16, v188
	v_and_b32_e32 v142, 0xffff0000, v189
	v_lshlrev_b32_e32 v148, 16, v189
	v_pk_fma_f32 v[34:35], v[122:123], v[140:141], v[124:125]
	v_lshlrev_b32_e32 v60, 16, v190
	v_pk_fma_f32 v[34:35], v[126:127], v[170:171], v[34:35]
	v_and_b32_e32 v54, 0xffff0000, v190
	v_and_b32_e32 v36, 0xffff0000, v191
	v_lshlrev_b32_e32 v48, 16, v191
	s_waitcnt vmcnt(10)
	v_lshlrev_b32_e32 v169, 16, v220
	v_pk_fma_f32 v[34:35], v[128:129], v[168:169], v[34:35]
	v_and_b32_e32 v163, 0xffff0000, v220
	v_mul_f32_e32 v0, 0x3d372713, v35
	v_mul_f32_e32 v0, v35, v0
	v_fma_f32 v0, v35, v0, v35
	v_mul_f32_e32 v0, 0x3f4c422a, v0
	v_mul_f32_e32 v0, -2.0, v0
	v_mul_f32_e32 v0, 0x3fb8aa3b, v0
	v_exp_f32_e32 v0, v0
	v_lshlrev_b32_e32 v149, 16, v221
	v_and_b32_e32 v143, 0xffff0000, v221
	v_and_b32_e32 v55, 0xffff0000, v222
	v_add_f32_e32 v0, 1.0, v0
	v_rcp_f32_e32 v0, v0
	v_lshlrev_b32_e32 v61, 16, v222
	v_and_b32_e32 v37, 0xffff0000, v223
	v_lshlrev_b32_e32 v49, 16, v223
	global_load_dwordx4 v[188:191], v[232:233], off
	global_load_dwordx4 v[220:223], v[234:235], off
	v_lshl_add_u64 v[232:233], v[232:233], 0, s[22:23]
	v_lshl_add_u64 v[234:235], v[234:235], 0, s[22:23]
	v_mul_f32_e32 v0, v35, v0
	v_mul_f32_e32 v0, v34, v0
	v_pk_fma_f32 v[34:35], v[6:7], v[138:139], v[30:31]
	s_nop 0
	v_pk_fma_f32 v[34:35], v[14:15], v[164:165], v[34:35]
	s_nop 0
	v_pk_fma_f32 v[34:35], v[22:23], v[162:163], v[34:35]
	s_nop 0
	v_mul_f32_e32 v38, 0x3d372713, v35
	v_mul_f32_e32 v38, v35, v38
	v_fma_f32 v38, v35, v38, v35
	v_mul_f32_e32 v38, 0x3f4c422a, v38
	v_mul_f32_e32 v38, -2.0, v38
	v_mul_f32_e32 v38, 0x3fb8aa3b, v38
	v_exp_f32_e32 v38, v38
	s_nop 0
	v_add_f32_e32 v38, 1.0, v38
	v_rcp_f32_e32 v38, v38
	s_nop 0
	v_mul_f32_e32 v35, v35, v38
	v_mul_f32_e32 v38, v34, v35
	v_pk_fma_f32 v[34:35], v[82:83], v[136:137], v[86:87]
	v_cvt_pk_bf16_f32 v38, v0, v38
	s_nop 0
	v_pk_fma_f32 v[34:35], v[90:91], v[150:151], v[34:35]
	s_nop 0
	v_pk_fma_f32 v[34:35], v[94:95], v[148:149], v[34:35]
	s_nop 0
	v_mul_f32_e32 v39, 0x3d372713, v35
	v_mul_f32_e32 v39, v35, v39
	v_fma_f32 v39, v35, v39, v35
	v_mul_f32_e32 v39, 0x3f4c422a, v39
	v_mul_f32_e32 v39, -2.0, v39
	v_mul_f32_e32 v39, 0x3fb8aa3b, v39
	v_exp_f32_e32 v39, v39
	s_nop 0
	v_add_f32_e32 v39, 1.0, v39
	v_rcp_f32_e32 v39, v39
	s_nop 0
	v_mul_f32_e32 v35, v35, v39
	v_mul_f32_e32 v39, v34, v35
	v_pk_fma_f32 v[34:35], v[8:9], v[134:135], v[32:33]
	s_nop 0
	v_pk_fma_f32 v[34:35], v[16:17], v[144:145], v[34:35]
	s_nop 0
	v_pk_fma_f32 v[34:35], v[24:25], v[142:143], v[34:35]
	s_nop 0
	v_mul_f32_e32 v40, 0x3d372713, v35
	v_mul_f32_e32 v40, v35, v40
	v_fma_f32 v40, v35, v40, v35
	v_mul_f32_e32 v40, 0x3f4c422a, v40
	v_mul_f32_e32 v40, -2.0, v40
	v_mul_f32_e32 v40, 0x3fb8aa3b, v40
	v_exp_f32_e32 v40, v40
	s_nop 0
	v_add_f32_e32 v40, 1.0, v40
	v_rcp_f32_e32 v40, v40
	s_nop 0
	v_mul_f32_e32 v35, v35, v40
	v_mul_f32_e32 v40, v34, v35
	v_pk_fma_f32 v[34:35], v[84:85], v[132:133], v[88:89]
	v_cvt_pk_bf16_f32 v39, v39, v40
	s_nop 0
	v_pk_fma_f32 v[34:35], v[92:93], v[62:63], v[34:35]
	s_nop 0
	v_pk_fma_f32 v[34:35], v[96:97], v[60:61], v[34:35]
	s_nop 0
	v_mul_f32_e32 v41, 0x3d372713, v35
	v_mul_f32_e32 v41, v35, v41
	v_fma_f32 v41, v35, v41, v35
	v_mul_f32_e32 v41, 0x3f4c422a, v41
	v_mul_f32_e32 v41, -2.0, v41
	v_mul_f32_e32 v41, 0x3fb8aa3b, v41
	v_exp_f32_e32 v41, v41
	s_nop 0
	v_add_f32_e32 v41, 1.0, v41
	v_rcp_f32_e32 v41, v41
	s_nop 0
	v_mul_f32_e32 v35, v35, v41
	v_mul_f32_e32 v41, v34, v35
	v_pk_fma_f32 v[34:35], v[2:3], v[130:131], v[26:27]
	s_nop 0
	v_pk_fma_f32 v[34:35], v[10:11], v[58:59], v[34:35]
	s_nop 0
	v_pk_fma_f32 v[34:35], v[18:19], v[54:55], v[34:35]
	s_nop 0
	v_mul_f32_e32 v44, 0x3d372713, v35
	v_mul_f32_e32 v44, v35, v44
	v_fma_f32 v44, v35, v44, v35
	v_mul_f32_e32 v44, 0x3f4c422a, v44
	v_mul_f32_e32 v44, -2.0, v44
	v_mul_f32_e32 v44, 0x3fb8aa3b, v44
	v_exp_f32_e32 v44, v44
	s_nop 0
	v_add_f32_e32 v44, 1.0, v44
	v_rcp_f32_e32 v44, v44
	s_nop 0
	v_mul_f32_e32 v35, v35, v44
	v_mul_f32_e32 v44, v34, v35
	v_pk_fma_f32 v[34:35], v[66:67], v[80:81], v[70:71]
	v_cvt_pk_bf16_f32 v40, v41, v44
	s_nop 0
	v_pk_fma_f32 v[34:35], v[74:75], v[50:51], v[34:35]
	s_nop 0
	v_pk_fma_f32 v[34:35], v[78:79], v[48:49], v[34:35]
	s_nop 0
	v_mul_f32_e32 v45, 0x3d372713, v35
	v_mul_f32_e32 v45, v35, v45
	v_fma_f32 v45, v35, v45, v35
	v_mul_f32_e32 v45, 0x3f4c422a, v45
	v_mul_f32_e32 v45, -2.0, v45
	v_mul_f32_e32 v45, 0x3fb8aa3b, v45
	v_exp_f32_e32 v45, v45
	s_nop 0
	v_add_f32_e32 v45, 1.0, v45
	v_rcp_f32_e32 v45, v45
	s_nop 0
	v_mul_f32_e32 v35, v35, v45
	v_mul_f32_e32 v45, v34, v35
	v_pk_fma_f32 v[34:35], v[4:5], v[76:77], v[28:29]
	s_nop 0
	v_pk_fma_f32 v[34:35], v[12:13], v[42:43], v[34:35]
	s_nop 0
	v_pk_fma_f32 v[34:35], v[20:21], v[36:37], v[34:35]
	s_nop 0
	v_mul_f32_e32 v46, 0x3d372713, v35
	v_mul_f32_e32 v46, v35, v46
	v_fma_f32 v46, v35, v46, v35
	v_mul_f32_e32 v46, 0x3f4c422a, v46
	v_mul_f32_e32 v46, -2.0, v46
	v_mul_f32_e32 v46, 0x3fb8aa3b, v46
	v_exp_f32_e32 v46, v46
	s_nop 0
	v_add_f32_e32 v46, 1.0, v46
	v_rcp_f32_e32 v46, v46
	s_nop 0
	v_mul_f32_e32 v35, v35, v46
	v_mul_f32_e32 v34, v34, v35
	v_cvt_pk_bf16_f32 v41, v45, v34
	v_mad_i64_i32 v[34:35], s[8:9], s16, v213, v[106:107]
	s_add_i32 s16, s13, 3
	s_add_i32 s8, s12, 0x8400
	s_mul_hi_i32 s9, s16, 0x2c00
	s_add_u32 s8, s80, s8
	s_addc_u32 s9, s81, s9
	global_store_dwordx4 v[34:35], v[38:41], off
	v_lshl_add_u64 v[34:35], s[8:9], 0, v[104:105]
	v_add_co_u32_e32 v34, vcc, s33, v34
	s_waitcnt vmcnt(10)
	v_and_b32_e32 v152, 0xffff0000, v224
	v_addc_co_u32_e32 v35, vcc, 0, v35, vcc
	v_lshlrev_b32_e32 v166, 16, v224
	v_and_b32_e32 v64, 0xffff0000, v225
	v_lshlrev_b32_e32 v146, 16, v225
	v_pk_fma_f32 v[38:39], v[122:123], v[170:171], v[124:125]
	v_and_b32_e32 v52, 0xffff0000, v226
	v_pk_fma_f32 v[38:39], v[126:127], v[168:169], v[38:39]
	v_lshlrev_b32_e32 v56, 16, v226
	v_and_b32_e32 v34, 0xffff0000, v227
	s_waitcnt vmcnt(10)
	v_lshlrev_b32_e32 v167, 16, v228
	v_pk_fma_f32 v[38:39], v[128:129], v[166:167], v[38:39]
	v_and_b32_e32 v153, 0xffff0000, v228
	v_mul_f32_e32 v0, 0x3d372713, v39
	v_mul_f32_e32 v0, v39, v0
	v_fma_f32 v0, v39, v0, v39
	v_mul_f32_e32 v0, 0x3f4c422a, v0
	v_mul_f32_e32 v0, -2.0, v0
	v_mul_f32_e32 v0, 0x3fb8aa3b, v0
	v_exp_f32_e32 v0, v0
	v_lshlrev_b32_e32 v147, 16, v229
	v_lshlrev_b32_e32 v44, 16, v227
	v_and_b32_e32 v65, 0xffff0000, v229
	v_add_f32_e32 v0, 1.0, v0
	v_rcp_f32_e32 v0, v0
	v_and_b32_e32 v53, 0xffff0000, v230
	v_lshlrev_b32_e32 v57, 16, v230
	v_and_b32_e32 v35, 0xffff0000, v231
	v_mul_f32_e32 v0, v39, v0
	v_mul_f32_e32 v0, v38, v0
	v_pk_fma_f32 v[38:39], v[6:7], v[164:165], v[30:31]
	v_lshlrev_b32_e32 v45, 16, v231
	global_load_dwordx4 v[224:227], v[232:233], off
	global_load_dwordx4 v[228:231], v[234:235], off
	v_lshl_add_u64 v[232:233], v[232:233], 0, s[22:23]
	v_lshl_add_u64 v[234:235], v[234:235], 0, s[22:23]
	v_pk_fma_f32 v[38:39], v[14:15], v[162:163], v[38:39]
	s_nop 0
	v_pk_fma_f32 v[38:39], v[22:23], v[152:153], v[38:39]
	s_nop 0
	v_mul_f32_e32 v40, 0x3d372713, v39
	v_mul_f32_e32 v40, v39, v40
	v_fma_f32 v40, v39, v40, v39
	v_mul_f32_e32 v40, 0x3f4c422a, v40
	v_mul_f32_e32 v40, -2.0, v40
	v_mul_f32_e32 v40, 0x3fb8aa3b, v40
	v_exp_f32_e32 v40, v40
	s_nop 0
	v_add_f32_e32 v40, 1.0, v40
	v_rcp_f32_e32 v40, v40
	s_nop 0
	v_mul_f32_e32 v39, v39, v40
	v_mul_f32_e32 v40, v38, v39
	v_pk_fma_f32 v[38:39], v[82:83], v[150:151], v[86:87]
	s_nop 0
	v_pk_fma_f32 v[38:39], v[90:91], v[148:149], v[38:39]
	s_nop 0
	v_pk_fma_f32 v[38:39], v[94:95], v[146:147], v[38:39]
	s_nop 0
	v_mul_f32_e32 v41, 0x3d372713, v39
	v_mul_f32_e32 v41, v39, v41
	v_fma_f32 v41, v39, v41, v39
	v_mul_f32_e32 v41, 0x3f4c422a, v41
	v_mul_f32_e32 v41, -2.0, v41
	v_mul_f32_e32 v41, 0x3fb8aa3b, v41
	v_exp_f32_e32 v41, v41
	s_nop 0
	v_add_f32_e32 v41, 1.0, v41
	v_rcp_f32_e32 v41, v41
	s_nop 0
	v_mul_f32_e32 v39, v39, v41
	v_mul_f32_e32 v41, v38, v39
	v_pk_fma_f32 v[38:39], v[8:9], v[144:145], v[32:33]
	s_nop 0
	v_pk_fma_f32 v[38:39], v[16:17], v[142:143], v[38:39]
	s_nop 0
	v_pk_fma_f32 v[38:39], v[24:25], v[64:65], v[38:39]
	s_nop 0
	v_mul_f32_e32 v46, 0x3d372713, v39
	v_mul_f32_e32 v46, v39, v46
	v_fma_f32 v46, v39, v46, v39
	v_mul_f32_e32 v46, 0x3f4c422a, v46
	v_mul_f32_e32 v46, -2.0, v46
	v_mul_f32_e32 v46, 0x3fb8aa3b, v46
	v_exp_f32_e32 v46, v46
	s_nop 0
	v_add_f32_e32 v46, 1.0, v46
	v_rcp_f32_e32 v46, v46
	s_nop 0
	v_mul_f32_e32 v39, v39, v46
	v_mul_f32_e32 v46, v38, v39
	v_pk_fma_f32 v[38:39], v[84:85], v[62:63], v[88:89]
	s_nop 0
	v_pk_fma_f32 v[38:39], v[92:93], v[60:61], v[38:39]
	s_nop 0
	v_pk_fma_f32 v[38:39], v[96:97], v[56:57], v[38:39]
	s_nop 0
	v_mul_f32_e32 v47, 0x3d372713, v39
	v_mul_f32_e32 v47, v39, v47
	v_fma_f32 v47, v39, v47, v39
	v_mul_f32_e32 v47, 0x3f4c422a, v47
	v_mul_f32_e32 v47, -2.0, v47
	v_mul_f32_e32 v47, 0x3fb8aa3b, v47
	v_exp_f32_e32 v47, v47
	s_nop 0
	v_add_f32_e32 v47, 1.0, v47
	v_rcp_f32_e32 v47, v47
	s_nop 0
	v_mul_f32_e32 v39, v39, v47
	v_mul_f32_e32 v47, v38, v39
	v_pk_fma_f32 v[38:39], v[2:3], v[58:59], v[26:27]
	s_nop 0
	v_pk_fma_f32 v[38:39], v[10:11], v[54:55], v[38:39]
	s_nop 0
	v_pk_fma_f32 v[38:39], v[18:19], v[52:53], v[38:39]
	s_nop 0
	v_mul_f32_e32 v58, 0x3d372713, v39
	v_mul_f32_e32 v58, v39, v58
	v_fma_f32 v58, v39, v58, v39
	v_mul_f32_e32 v58, 0x3f4c422a, v58
	v_mul_f32_e32 v58, -2.0, v58
	v_mul_f32_e32 v58, 0x3fb8aa3b, v58
	v_exp_f32_e32 v58, v58
	s_nop 0
	v_add_f32_e32 v58, 1.0, v58
	v_rcp_f32_e32 v58, v58
	s_nop 0
	v_mul_f32_e32 v39, v39, v58
	v_mul_f32_e32 v58, v38, v39
	v_pk_fma_f32 v[38:39], v[66:67], v[50:51], v[70:71]
	s_nop 0
	v_pk_fma_f32 v[38:39], v[74:75], v[48:49], v[38:39]
	s_nop 0
	v_pk_fma_f32 v[38:39], v[78:79], v[44:45], v[38:39]
	s_nop 0
	v_mul_f32_e32 v50, 0x3d372713, v39
	v_mul_f32_e32 v50, v39, v50
	v_fma_f32 v50, v39, v50, v39
	v_mul_f32_e32 v50, 0x3f4c422a, v50
	v_mul_f32_e32 v50, -2.0, v50
	v_mul_f32_e32 v50, 0x3fb8aa3b, v50
	v_exp_f32_e32 v50, v50
	s_nop 0
	v_add_f32_e32 v50, 1.0, v50
	v_rcp_f32_e32 v50, v50
	s_nop 0
	v_mul_f32_e32 v39, v39, v50
	v_mul_f32_e32 v50, v38, v39
	v_pk_fma_f32 v[38:39], v[4:5], v[42:43], v[28:29]
	s_nop 0
	v_pk_fma_f32 v[38:39], v[12:13], v[36:37], v[38:39]
	v_pk_fma_f32 v[36:37], v[4:5], v[36:37], v[28:29]
	v_pk_fma_f32 v[38:39], v[20:21], v[34:35], v[38:39]
	v_pk_fma_f32 v[36:37], v[12:13], v[34:35], v[36:37]
	v_mul_f32_e32 v42, 0x3d372713, v39
	v_mul_f32_e32 v42, v39, v42
	v_fma_f32 v42, v39, v42, v39
	v_mul_f32_e32 v42, 0x3f4c422a, v42
	v_mul_f32_e32 v42, -2.0, v42
	v_mul_f32_e32 v42, 0x3fb8aa3b, v42
	v_exp_f32_e32 v42, v42
	v_pk_fma_f32 v[34:35], v[4:5], v[34:35], v[28:29]
	v_add_f32_e32 v42, 1.0, v42
	v_rcp_f32_e32 v42, v42
	s_nop 0
	v_mul_f32_e32 v39, v39, v42
	v_mul_f32_e32 v42, v38, v39
	v_cvt_pk_bf16_f32 v39, v41, v46
	v_cvt_pk_bf16_f32 v41, v50, v42
	v_mad_i64_i32 v[42:43], s[8:9], s16, v213, v[106:107]
	s_add_i32 s16, s13, 4
	s_add_i32 s8, s12, 0xb000
	s_mul_hi_i32 s9, s16, 0x2c00
	s_add_u32 s8, s80, s8
	s_addc_u32 s9, s81, s9
	v_cvt_pk_bf16_f32 v38, v0, v40
	v_cvt_pk_bf16_f32 v40, v47, v58
	global_store_dwordx4 v[42:43], v[38:41], off
	v_lshl_add_u64 v[42:43], s[8:9], 0, v[104:105]
	v_add_co_u32_e32 v42, vcc, s33, v42
	s_waitcnt vmcnt(10)
	v_lshlrev_b32_e32 v150, 16, v172
	v_addc_co_u32_e32 v43, vcc, 0, v43, vcc
	v_pk_fma_f32 v[42:43], v[122:123], v[168:169], v[124:125]
	v_and_b32_e32 v144, 0xffff0000, v172
	v_pk_fma_f32 v[42:43], v[126:127], v[166:167], v[42:43]
	v_lshlrev_b32_e32 v140, 16, v173
	v_and_b32_e32 v62, 0xffff0000, v173
	v_lshlrev_b32_e32 v50, 16, v174
	v_and_b32_e32 v46, 0xffff0000, v174
	v_and_b32_e32 v38, 0xffff0000, v175
	v_lshlrev_b32_e32 v40, 16, v175
	s_waitcnt vmcnt(10)
	v_lshlrev_b32_e32 v151, 16, v176
	v_pk_fma_f32 v[42:43], v[128:129], v[150:151], v[42:43]
	v_and_b32_e32 v145, 0xffff0000, v176
	v_mul_f32_e32 v0, 0x3d372713, v43
	v_mul_f32_e32 v0, v43, v0
	v_fma_f32 v0, v43, v0, v43
	v_mul_f32_e32 v0, 0x3f4c422a, v0
	v_mul_f32_e32 v0, -2.0, v0
	v_mul_f32_e32 v0, 0x3fb8aa3b, v0
	v_exp_f32_e32 v0, v0
	v_lshlrev_b32_e32 v141, 16, v177
	v_and_b32_e32 v63, 0xffff0000, v177
	v_lshlrev_b32_e32 v51, 16, v178
	v_add_f32_e32 v0, 1.0, v0
	v_rcp_f32_e32 v0, v0
	v_and_b32_e32 v47, 0xffff0000, v178
	v_lshlrev_b32_e32 v41, 16, v179
	v_and_b32_e32 v39, 0xffff0000, v179
	global_load_dwordx4 v[172:175], v[232:233], off
	global_load_dwordx4 v[176:179], v[234:235], off
	v_lshl_add_u64 v[232:233], v[232:233], 0, s[22:23]
	v_lshl_add_u64 v[234:235], v[234:235], 0, s[22:23]
	v_mul_f32_e32 v0, v43, v0
	v_mul_f32_e32 v0, v42, v0
	v_pk_fma_f32 v[42:43], v[6:7], v[162:163], v[30:31]
	v_pk_fma_f32 v[36:37], v[20:21], v[38:39], v[36:37]
	v_pk_fma_f32 v[42:43], v[14:15], v[152:153], v[42:43]
	v_pk_fma_f32 v[34:35], v[12:13], v[38:39], v[34:35]
	v_pk_fma_f32 v[42:43], v[22:23], v[144:145], v[42:43]
	v_pk_fma_f32 v[38:39], v[4:5], v[38:39], v[28:29]
	v_mul_f32_e32 v58, 0x3d372713, v43
	v_mul_f32_e32 v58, v43, v58
	v_fma_f32 v58, v43, v58, v43
	v_mul_f32_e32 v58, 0x3f4c422a, v58
	v_mul_f32_e32 v58, -2.0, v58
	v_mul_f32_e32 v58, 0x3fb8aa3b, v58
	v_exp_f32_e32 v58, v58
	s_nop 0
	v_add_f32_e32 v58, 1.0, v58
	v_rcp_f32_e32 v58, v58
	s_nop 0
	v_mul_f32_e32 v43, v43, v58
	v_mul_f32_e32 v58, v42, v43
	v_pk_fma_f32 v[42:43], v[82:83], v[148:149], v[86:87]
	v_cvt_pk_bf16_f32 v58, v0, v58
	s_nop 0
	v_pk_fma_f32 v[42:43], v[90:91], v[146:147], v[42:43]
	s_nop 0
	v_pk_fma_f32 v[42:43], v[94:95], v[140:141], v[42:43]
	s_nop 0
	v_mul_f32_e32 v59, 0x3d372713, v43
	v_mul_f32_e32 v59, v43, v59
	v_fma_f32 v59, v43, v59, v43
	v_mul_f32_e32 v59, 0x3f4c422a, v59
	v_mul_f32_e32 v59, -2.0, v59
	v_mul_f32_e32 v59, 0x3fb8aa3b, v59
	v_exp_f32_e32 v59, v59
	s_nop 0
	v_add_f32_e32 v59, 1.0, v59
	v_rcp_f32_e32 v59, v59
	s_nop 0
	v_mul_f32_e32 v43, v43, v59
	v_mul_f32_e32 v59, v42, v43
	v_pk_fma_f32 v[42:43], v[8:9], v[142:143], v[32:33]
	s_nop 0
	v_pk_fma_f32 v[42:43], v[16:17], v[64:65], v[42:43]
	s_nop 0
	v_pk_fma_f32 v[42:43], v[24:25], v[62:63], v[42:43]
	s_nop 0
	v_mul_f32_e32 v76, 0x3d372713, v43
	v_mul_f32_e32 v76, v43, v76
	v_fma_f32 v76, v43, v76, v43
	v_mul_f32_e32 v76, 0x3f4c422a, v76
	v_mul_f32_e32 v76, -2.0, v76
	v_mul_f32_e32 v76, 0x3fb8aa3b, v76
	v_exp_f32_e32 v76, v76
	s_nop 0
	v_add_f32_e32 v76, 1.0, v76
	v_rcp_f32_e32 v76, v76
	s_nop 0
	v_mul_f32_e32 v43, v43, v76
	v_mul_f32_e32 v76, v42, v43
	v_pk_fma_f32 v[42:43], v[84:85], v[60:61], v[88:89]
	v_cvt_pk_bf16_f32 v59, v59, v76
	s_nop 0
	v_pk_fma_f32 v[42:43], v[92:93], v[56:57], v[42:43]
	s_nop 0
	v_pk_fma_f32 v[42:43], v[96:97], v[50:51], v[42:43]
	s_nop 0
	v_mul_f32_e32 v60, 0x3d372713, v43
	v_mul_f32_e32 v60, v43, v60
	v_fma_f32 v60, v43, v60, v43
	v_mul_f32_e32 v60, 0x3f4c422a, v60
	v_mul_f32_e32 v60, -2.0, v60
	v_mul_f32_e32 v60, 0x3fb8aa3b, v60
	v_exp_f32_e32 v60, v60
	s_nop 0
	v_add_f32_e32 v60, 1.0, v60
	v_rcp_f32_e32 v60, v60
	s_nop 0
	v_mul_f32_e32 v43, v43, v60
	v_mul_f32_e32 v60, v42, v43
	v_pk_fma_f32 v[42:43], v[2:3], v[54:55], v[26:27]
	s_nop 0
	v_pk_fma_f32 v[42:43], v[10:11], v[52:53], v[42:43]
	s_nop 0
	v_pk_fma_f32 v[42:43], v[18:19], v[46:47], v[42:43]
	s_nop 0
	v_mul_f32_e32 v54, 0x3d372713, v43
	v_mul_f32_e32 v54, v43, v54
	v_fma_f32 v54, v43, v54, v43
	v_mul_f32_e32 v54, 0x3f4c422a, v54
	v_mul_f32_e32 v54, -2.0, v54
	v_mul_f32_e32 v54, 0x3fb8aa3b, v54
	v_exp_f32_e32 v54, v54
	s_nop 0
	v_add_f32_e32 v54, 1.0, v54
	v_rcp_f32_e32 v54, v54
	s_nop 0
	v_mul_f32_e32 v43, v43, v54
	v_mul_f32_e32 v54, v42, v43
	v_pk_fma_f32 v[42:43], v[66:67], v[48:49], v[70:71]
	v_cvt_pk_bf16_f32 v60, v60, v54
	s_nop 0
	v_pk_fma_f32 v[42:43], v[74:75], v[44:45], v[42:43]
	s_nop 0
	v_pk_fma_f32 v[42:43], v[78:79], v[40:41], v[42:43]
	s_nop 0
	v_mul_f32_e32 v48, 0x3d372713, v43
	v_mul_f32_e32 v48, v43, v48
	v_fma_f32 v48, v43, v48, v43
	v_mul_f32_e32 v48, 0x3f4c422a, v48
	v_mul_f32_e32 v48, -2.0, v48
	v_mul_f32_e32 v48, 0x3fb8aa3b, v48
	v_exp_f32_e32 v48, v48
	s_nop 0
	v_add_f32_e32 v48, 1.0, v48
	v_rcp_f32_e32 v48, v48
	s_nop 0
	v_mul_f32_e32 v43, v43, v48
	v_mul_f32_e32 v42, v42, v43
	v_mul_f32_e32 v43, 0x3d372713, v37
	v_mul_f32_e32 v43, v37, v43
	v_fma_f32 v43, v37, v43, v37
	v_mul_f32_e32 v43, 0x3f4c422a, v43
	v_mul_f32_e32 v43, -2.0, v43
	v_mul_f32_e32 v43, 0x3fb8aa3b, v43
	v_exp_f32_e32 v43, v43
	s_nop 0
	v_add_f32_e32 v43, 1.0, v43
	v_rcp_f32_e32 v43, v43
	s_nop 0
	v_mul_f32_e32 v37, v37, v43
	v_mul_f32_e32 v36, v36, v37
	v_cvt_pk_bf16_f32 v61, v42, v36
	v_mad_i64_i32 v[36:37], s[8:9], s16, v213, v[106:107]
	s_add_i32 s16, s13, 5
	s_add_i32 s8, s12, 0xdc00
	s_mul_hi_i32 s9, s16, 0x2c00
	s_add_u32 s8, s80, s8
	s_addc_u32 s9, s81, s9
	global_store_dwordx4 v[36:37], v[58:61], off
	v_lshl_add_u64 v[36:37], s[8:9], 0, v[104:105]
	v_add_co_u32_e32 v36, vcc, s33, v36
	s_waitcnt vmcnt(10)
	v_lshlrev_b32_e32 v142, 16, v180
	v_addc_co_u32_e32 v37, vcc, 0, v37, vcc
	v_pk_fma_f32 v[36:37], v[122:123], v[166:167], v[124:125]
	v_and_b32_e32 v138, 0xffff0000, v180
	v_pk_fma_f32 v[36:37], v[126:127], v[150:151], v[36:37]
	v_lshlrev_b32_e32 v136, 16, v181
	v_and_b32_e32 v134, 0xffff0000, v181
	v_lshlrev_b32_e32 v132, 16, v182
	v_and_b32_e32 v130, 0xffff0000, v182
	v_lshlrev_b32_e32 v80, 16, v183
	v_and_b32_e32 v76, 0xffff0000, v183
	s_waitcnt vmcnt(10)
	v_lshlrev_b32_e32 v143, 16, v184
	v_pk_fma_f32 v[36:37], v[128:129], v[142:143], v[36:37]
	v_and_b32_e32 v139, 0xffff0000, v184
	v_mul_f32_e32 v0, 0x3d372713, v37
	v_mul_f32_e32 v0, v37, v0
	v_fma_f32 v0, v37, v0, v37
	v_mul_f32_e32 v0, 0x3f4c422a, v0
	v_mul_f32_e32 v0, -2.0, v0
	v_mul_f32_e32 v0, 0x3fb8aa3b, v0
	v_exp_f32_e32 v0, v0
	v_lshlrev_b32_e32 v137, 16, v185
	v_and_b32_e32 v135, 0xffff0000, v185
	v_lshlrev_b32_e32 v133, 16, v186
	v_add_f32_e32 v0, 1.0, v0
	v_rcp_f32_e32 v0, v0
	v_and_b32_e32 v131, 0xffff0000, v186
	v_lshlrev_b32_e32 v81, 16, v187
	v_and_b32_e32 v77, 0xffff0000, v187
	global_load_dwordx4 v[180:183], v[232:233], off
	global_load_dwordx4 v[184:187], v[234:235], off
	v_lshl_add_u64 v[232:233], v[232:233], 0, s[22:23]
	v_lshl_add_u64 v[234:235], v[234:235], 0, s[22:23]
	v_mul_f32_e32 v0, v37, v0
	v_mul_f32_e32 v0, v36, v0
	v_pk_fma_f32 v[36:37], v[6:7], v[152:153], v[30:31]
	v_pk_fma_f32 v[34:35], v[20:21], v[76:77], v[34:35]
	v_pk_fma_f32 v[36:37], v[14:15], v[144:145], v[36:37]
	v_pk_fma_f32 v[38:39], v[12:13], v[76:77], v[38:39]
	v_pk_fma_f32 v[36:37], v[22:23], v[138:139], v[36:37]
	v_pk_fma_f32 v[76:77], v[4:5], v[76:77], v[28:29]
	v_mul_f32_e32 v42, 0x3d372713, v37
	v_mul_f32_e32 v42, v37, v42
	v_fma_f32 v42, v37, v42, v37
	v_mul_f32_e32 v42, 0x3f4c422a, v42
	v_mul_f32_e32 v42, -2.0, v42
	v_mul_f32_e32 v42, 0x3fb8aa3b, v42
	v_exp_f32_e32 v42, v42
	s_nop 0
	v_add_f32_e32 v42, 1.0, v42
	v_rcp_f32_e32 v42, v42
	s_nop 0
	v_mul_f32_e32 v37, v37, v42
	v_mul_f32_e32 v42, v36, v37
	v_pk_fma_f32 v[36:37], v[82:83], v[146:147], v[86:87]
	s_nop 0
	v_pk_fma_f32 v[36:37], v[90:91], v[140:141], v[36:37]
	s_nop 0
	v_pk_fma_f32 v[36:37], v[94:95], v[136:137], v[36:37]
	s_nop 0
	v_mul_f32_e32 v43, 0x3d372713, v37
	v_mul_f32_e32 v43, v37, v43
	v_fma_f32 v43, v37, v43, v37
	v_mul_f32_e32 v43, 0x3f4c422a, v43
	v_mul_f32_e32 v43, -2.0, v43
	v_mul_f32_e32 v43, 0x3fb8aa3b, v43
	v_exp_f32_e32 v43, v43
	s_nop 0
	v_add_f32_e32 v43, 1.0, v43
	v_rcp_f32_e32 v43, v43
	s_nop 0
	v_mul_f32_e32 v37, v37, v43
	v_mul_f32_e32 v43, v36, v37
	v_pk_fma_f32 v[36:37], v[8:9], v[64:65], v[32:33]
	s_nop 0
	v_pk_fma_f32 v[36:37], v[16:17], v[62:63], v[36:37]
	s_nop 0
	v_pk_fma_f32 v[36:37], v[24:25], v[134:135], v[36:37]
	s_nop 0
	v_mul_f32_e32 v48, 0x3d372713, v37
	v_mul_f32_e32 v48, v37, v48
	v_fma_f32 v48, v37, v48, v37
	v_mul_f32_e32 v48, 0x3f4c422a, v48
	v_mul_f32_e32 v48, -2.0, v48
	v_mul_f32_e32 v48, 0x3fb8aa3b, v48
	v_exp_f32_e32 v48, v48
	s_nop 0
	v_add_f32_e32 v48, 1.0, v48
	v_rcp_f32_e32 v48, v48
	s_nop 0
	v_mul_f32_e32 v37, v37, v48
	v_mul_f32_e32 v48, v36, v37
	v_pk_fma_f32 v[36:37], v[84:85], v[56:57], v[88:89]
	s_nop 0
	v_pk_fma_f32 v[36:37], v[92:93], v[50:51], v[36:37]
	s_nop 0
	v_pk_fma_f32 v[36:37], v[96:97], v[132:133], v[36:37]
	s_nop 0
	v_mul_f32_e32 v49, 0x3d372713, v37
	v_mul_f32_e32 v49, v37, v49
	v_fma_f32 v49, v37, v49, v37
	v_mul_f32_e32 v49, 0x3f4c422a, v49
	v_mul_f32_e32 v49, -2.0, v49
	v_mul_f32_e32 v49, 0x3fb8aa3b, v49
	v_exp_f32_e32 v49, v49
	s_nop 0
	v_add_f32_e32 v49, 1.0, v49
	v_rcp_f32_e32 v49, v49
	s_nop 0
	v_mul_f32_e32 v37, v37, v49
	v_mul_f32_e32 v49, v36, v37
	v_pk_fma_f32 v[36:37], v[2:3], v[52:53], v[26:27]
	s_nop 0
	v_pk_fma_f32 v[36:37], v[10:11], v[46:47], v[36:37]
	v_pk_fma_f32 v[46:47], v[2:3], v[46:47], v[26:27]
	v_pk_fma_f32 v[36:37], v[18:19], v[130:131], v[36:37]
	v_pk_fma_f32 v[46:47], v[10:11], v[130:131], v[46:47]
	v_mul_f32_e32 v52, 0x3d372713, v37
	v_mul_f32_e32 v52, v37, v52
	v_fma_f32 v52, v37, v52, v37
	v_mul_f32_e32 v52, 0x3f4c422a, v52
	v_mul_f32_e32 v52, -2.0, v52
	v_mul_f32_e32 v52, 0x3fb8aa3b, v52
	v_exp_f32_e32 v52, v52
	v_pk_fma_f32 v[130:131], v[2:3], v[130:131], v[26:27]
	v_add_f32_e32 v52, 1.0, v52
	v_rcp_f32_e32 v52, v52
	s_nop 0
	v_mul_f32_e32 v37, v37, v52
	v_mul_f32_e32 v52, v36, v37
	v_pk_fma_f32 v[36:37], v[66:67], v[44:45], v[70:71]
	s_nop 0
	v_pk_fma_f32 v[36:37], v[74:75], v[40:41], v[36:37]
	v_pk_fma_f32 v[40:41], v[66:67], v[40:41], v[70:71]
	v_pk_fma_f32 v[36:37], v[78:79], v[80:81], v[36:37]
	v_pk_fma_f32 v[40:41], v[74:75], v[80:81], v[40:41]
	v_mul_f32_e32 v44, 0x3d372713, v37
	v_mul_f32_e32 v44, v37, v44
	v_fma_f32 v44, v37, v44, v37
	v_mul_f32_e32 v44, 0x3f4c422a, v44
	v_mul_f32_e32 v44, -2.0, v44
	v_mul_f32_e32 v44, 0x3fb8aa3b, v44
	v_exp_f32_e32 v44, v44
	v_pk_fma_f32 v[80:81], v[66:67], v[80:81], v[70:71]
	v_add_f32_e32 v44, 1.0, v44
	v_rcp_f32_e32 v44, v44
	s_nop 0
	v_mul_f32_e32 v37, v37, v44
	v_mul_f32_e32 v37, v36, v37
	v_mul_f32_e32 v36, 0x3d372713, v35
	v_mul_f32_e32 v36, v35, v36
	v_fma_f32 v36, v35, v36, v35
	v_mul_f32_e32 v36, 0x3f4c422a, v36
	v_mul_f32_e32 v36, -2.0, v36
	v_mul_f32_e32 v36, 0x3fb8aa3b, v36
	v_exp_f32_e32 v36, v36
	s_nop 0
	v_add_f32_e32 v36, 1.0, v36
	v_rcp_f32_e32 v36, v36
	s_nop 0
	v_mul_f32_e32 v35, v35, v36
	v_mul_f32_e32 v44, v34, v35
	v_cvt_pk_bf16_f32 v34, v0, v42
	v_cvt_pk_bf16_f32 v35, v43, v48
	v_mad_i64_i32 v[42:43], s[8:9], s16, v213, v[106:107]
	s_add_i32 s16, s13, 6
	s_add_i32 s8, s12, 0x10800
	s_mul_hi_i32 s9, s16, 0x2c00
	s_add_u32 s8, s80, s8
	s_addc_u32 s9, s81, s9
	v_cvt_pk_bf16_f32 v36, v49, v52
	v_cvt_pk_bf16_f32 v37, v37, v44
	global_store_dwordx4 v[42:43], v[34:37], off
	v_pk_fma_f32 v[48:49], v[122:123], v[150:151], v[124:125]
	s_add_i32 s13, s13, 7
	v_lshl_add_u64 v[34:35], s[8:9], 0, v[104:105]
	v_add_co_u32_e32 v34, vcc, s33, v34
	v_pk_fma_f32 v[48:49], v[126:127], v[142:143], v[48:49]
	s_nop 0
	v_addc_co_u32_e32 v35, vcc, 0, v35, vcc
	s_add_i32 s12, s12, 0x13400
	v_pk_fma_f32 v[142:143], v[122:123], v[142:143], v[124:125]
	s_waitcnt vmcnt(10)
	v_lshlrev_b32_e32 v54, 16, v188
	v_and_b32_e32 v55, 0xffff0000, v188
	v_and_b32_e32 v57, 0xffff0000, v189
	v_lshlrev_b32_e32 v56, 16, v189
	v_and_b32_e32 v35, 0xffff0000, v190
	v_lshlrev_b32_e32 v34, 16, v190
	s_waitcnt vmcnt(10)
	v_lshlrev_b32_e32 v58, 16, v220
	v_and_b32_e32 v43, 0xffff0000, v222
	v_lshlrev_b32_e32 v42, 16, v222
	v_and_b32_e32 v37, 0xffff0000, v191
	v_lshlrev_b32_e32 v36, 16, v191
	v_and_b32_e32 v45, 0xffff0000, v223
	v_lshlrev_b32_e32 v44, 16, v223
	v_mov_b32_e32 v148, v54
	v_mov_b32_e32 v149, v58
	v_pk_fma_f32 v[48:49], v[128:129], v[148:149], v[48:49]
	v_and_b32_e32 v59, 0xffff0000, v220
	v_mul_f32_e32 v0, 0x3d372713, v49
	v_mul_f32_e32 v0, v49, v0
	v_fma_f32 v0, v49, v0, v49
	v_mul_f32_e32 v0, 0x3f4c422a, v0
	v_mul_f32_e32 v0, -2.0, v0
	v_mul_f32_e32 v0, 0x3fb8aa3b, v0
	v_exp_f32_e32 v0, v0
	v_mov_b32_e32 v150, v55
	v_mov_b32_e32 v151, v59
	v_lshlrev_b32_e32 v60, 16, v221
	v_add_f32_e32 v0, 1.0, v0
	v_rcp_f32_e32 v0, v0
	v_and_b32_e32 v61, 0xffff0000, v221
	global_load_dwordx4 v[188:191], v[232:233], off
	global_load_dwordx4 v[220:223], v[234:235], off
	v_lshl_add_u64 v[232:233], v[232:233], 0, s[22:23]
	v_lshl_add_u64 v[234:235], v[234:235], 0, s[22:23]
	v_mov_b32_e32 v152, v57
	v_mov_b32_e32 v153, v61
	v_mul_f32_e32 v0, v49, v0
	v_mul_f32_e32 v0, v48, v0
	v_pk_fma_f32 v[48:49], v[6:7], v[144:145], v[30:31]
	v_mov_b32_e32 v162, v34
	v_pk_fma_f32 v[48:49], v[14:15], v[138:139], v[48:49]
	v_mov_b32_e32 v163, v42
	v_pk_fma_f32 v[48:49], v[22:23], v[150:151], v[48:49]
	v_mov_b32_e32 v164, v35
	v_mul_f32_e32 v52, 0x3d372713, v49
	v_mul_f32_e32 v52, v49, v52
	v_fma_f32 v52, v49, v52, v49
	v_mul_f32_e32 v52, 0x3f4c422a, v52
	v_mul_f32_e32 v52, -2.0, v52
	v_mul_f32_e32 v52, 0x3fb8aa3b, v52
	v_exp_f32_e32 v52, v52
	v_mov_b32_e32 v165, v43
	v_pk_fma_f32 v[46:47], v[18:19], v[164:165], v[46:47]
	v_mov_b32_e32 v166, v36
	v_add_f32_e32 v52, 1.0, v52
	v_rcp_f32_e32 v52, v52
	v_mov_b32_e32 v167, v44
	v_pk_fma_f32 v[40:41], v[78:79], v[166:167], v[40:41]
	v_mov_b32_e32 v168, v37
	v_mul_f32_e32 v49, v49, v52
	v_mul_f32_e32 v52, v48, v49
	v_pk_fma_f32 v[48:49], v[82:83], v[140:141], v[86:87]
	v_mov_b32_e32 v140, v56
	v_pk_fma_f32 v[48:49], v[90:91], v[136:137], v[48:49]
	v_mov_b32_e32 v141, v60
	v_pk_fma_f32 v[48:49], v[94:95], v[140:141], v[48:49]
	v_mov_b32_e32 v169, v45
	v_mul_f32_e32 v53, 0x3d372713, v49
	v_mul_f32_e32 v53, v49, v53
	v_fma_f32 v53, v49, v53, v49
	v_mul_f32_e32 v53, 0x3f4c422a, v53
	v_mul_f32_e32 v53, -2.0, v53
	v_mul_f32_e32 v53, 0x3fb8aa3b, v53
	v_exp_f32_e32 v53, v53
	v_pk_fma_f32 v[38:39], v[20:21], v[168:169], v[38:39]
	v_pk_fma_f32 v[142:143], v[126:127], v[148:149], v[142:143]
	v_pk_fma_f32 v[138:139], v[6:7], v[138:139], v[30:31]
	v_add_f32_e32 v53, 1.0, v53
	v_rcp_f32_e32 v53, v53
	v_pk_fma_f32 v[138:139], v[14:15], v[150:151], v[138:139]
	v_pk_fma_f32 v[136:137], v[82:83], v[136:137], v[86:87]
	v_pk_fma_f32 v[130:131], v[10:11], v[164:165], v[130:131]
	v_mul_f32_e32 v49, v49, v53
	v_mul_f32_e32 v53, v48, v49
	v_pk_fma_f32 v[48:49], v[8:9], v[62:63], v[32:33]
	v_pk_fma_f32 v[136:137], v[90:91], v[140:141], v[136:137]
	v_pk_fma_f32 v[48:49], v[16:17], v[134:135], v[48:49]
	v_pk_fma_f32 v[134:135], v[8:9], v[134:135], v[32:33]
	v_pk_fma_f32 v[48:49], v[24:25], v[152:153], v[48:49]
	v_pk_fma_f32 v[134:135], v[16:17], v[152:153], v[134:135]
	v_mul_f32_e32 v62, 0x3d372713, v49
	v_mul_f32_e32 v62, v49, v62
	v_fma_f32 v62, v49, v62, v49
	v_mul_f32_e32 v62, 0x3f4c422a, v62
	v_mul_f32_e32 v62, -2.0, v62
	v_mul_f32_e32 v62, 0x3fb8aa3b, v62
	v_exp_f32_e32 v62, v62
	v_pk_fma_f32 v[80:81], v[74:75], v[166:167], v[80:81]
	v_pk_fma_f32 v[76:77], v[12:13], v[168:169], v[76:77]
	v_add_f32_e32 v62, 1.0, v62
	v_rcp_f32_e32 v62, v62
	s_nop 0
	v_mul_f32_e32 v49, v49, v62
	v_mul_f32_e32 v62, v48, v49
	v_pk_fma_f32 v[48:49], v[84:85], v[50:51], v[88:89]
	s_nop 0
	v_pk_fma_f32 v[48:49], v[92:93], v[132:133], v[48:49]
	v_pk_fma_f32 v[132:133], v[84:85], v[132:133], v[88:89]
	v_pk_fma_f32 v[48:49], v[96:97], v[162:163], v[48:49]
	v_pk_fma_f32 v[132:133], v[92:93], v[162:163], v[132:133]
	v_mul_f32_e32 v50, 0x3d372713, v49
	v_mul_f32_e32 v50, v49, v50
	v_fma_f32 v50, v49, v50, v49
	v_mul_f32_e32 v50, 0x3f4c422a, v50
	v_mul_f32_e32 v50, -2.0, v50
	v_mul_f32_e32 v50, 0x3fb8aa3b, v50
	v_exp_f32_e32 v50, v50
	s_nop 0
	v_add_f32_e32 v50, 1.0, v50
	v_rcp_f32_e32 v50, v50
	s_nop 0
	v_mul_f32_e32 v49, v49, v50
	v_mul_f32_e32 v48, v48, v49
	v_mul_f32_e32 v49, 0x3d372713, v47
	v_mul_f32_e32 v49, v47, v49
	v_fma_f32 v49, v47, v49, v47
	v_mul_f32_e32 v49, 0x3f4c422a, v49
	v_mul_f32_e32 v49, -2.0, v49
	v_mul_f32_e32 v49, 0x3fb8aa3b, v49
	v_exp_f32_e32 v49, v49
	s_nop 0
	v_add_f32_e32 v49, 1.0, v49
	v_rcp_f32_e32 v49, v49
	s_nop 0
	v_mul_f32_e32 v47, v47, v49
	v_mul_f32_e32 v46, v46, v47
	v_mul_f32_e32 v47, 0x3d372713, v41
	v_mul_f32_e32 v47, v41, v47
	v_fma_f32 v47, v41, v47, v41
	v_mul_f32_e32 v47, 0x3f4c422a, v47
	v_mul_f32_e32 v47, -2.0, v47
	v_mul_f32_e32 v47, 0x3fb8aa3b, v47
	v_exp_f32_e32 v47, v47
	s_nop 0
	v_add_f32_e32 v47, 1.0, v47
	v_rcp_f32_e32 v47, v47
	s_nop 0
	v_mul_f32_e32 v41, v41, v47
	v_mul_f32_e32 v41, v40, v41
	v_mul_f32_e32 v40, 0x3d372713, v39
	v_mul_f32_e32 v40, v39, v40
	v_fma_f32 v40, v39, v40, v39
	v_mul_f32_e32 v40, 0x3f4c422a, v40
	v_mul_f32_e32 v40, -2.0, v40
	v_mul_f32_e32 v40, 0x3fb8aa3b, v40
	v_exp_f32_e32 v40, v40
	s_nop 0
	v_add_f32_e32 v40, 1.0, v40
	v_rcp_f32_e32 v40, v40
	s_nop 0
	v_mul_f32_e32 v39, v39, v40
	v_mul_f32_e32 v47, v38, v39
	v_cvt_pk_bf16_f32 v40, v48, v46
	v_cvt_pk_bf16_f32 v41, v41, v47
	v_mad_i64_i32 v[46:47], s[8:9], s16, v213, v[106:107]
	s_mul_hi_i32 s9, s13, 0x2c00
	s_add_u32 s8, s80, s12
	s_addc_u32 s9, s81, s9
	v_cvt_pk_bf16_f32 v38, v0, v52
	v_cvt_pk_bf16_f32 v39, v53, v62
	global_store_dwordx4 v[46:47], v[38:41], off
	v_lshl_add_u64 v[46:47], s[8:9], 0, v[104:105]
	v_add_co_u32_e32 v46, vcc, s33, v46
	s_add_i32 s15, s15, 8
	s_nop 0
	v_addc_co_u32_e32 v47, vcc, 0, v47, vcc
	s_cmp_lg_u32 s14, s15
	s_waitcnt vmcnt(10)
	v_lshlrev_b32_e32 v62, 16, v224
	v_and_b32_e32 v63, 0xffff0000, v224
	v_lshlrev_b32_e32 v64, 16, v225
	v_and_b32_e32 v65, 0xffff0000, v225
	v_lshlrev_b32_e32 v50, 16, v226
	v_and_b32_e32 v51, 0xffff0000, v226
	s_waitcnt vmcnt(10)
	v_lshlrev_b32_e32 v46, 16, v228
	v_and_b32_e32 v47, 0xffff0000, v228
	v_and_b32_e32 v49, 0xffff0000, v229
	v_lshlrev_b32_e32 v48, 16, v229
	v_mov_b32_e32 v144, v62
	v_mov_b32_e32 v145, v46
	v_pk_fma_f32 v[142:143], v[128:129], v[144:145], v[142:143]
	v_lshlrev_b32_e32 v38, 16, v230
	v_mul_f32_e32 v0, 0x3d372713, v143
	v_mul_f32_e32 v0, v143, v0
	v_fma_f32 v0, v143, v0, v143
	v_mul_f32_e32 v0, 0x3f4c422a, v0
	v_mul_f32_e32 v0, -2.0, v0
	v_mul_f32_e32 v0, 0x3fb8aa3b, v0
	v_exp_f32_e32 v0, v0
	v_and_b32_e32 v39, 0xffff0000, v230
	v_lshlrev_b32_e32 v52, 16, v227
	v_lshlrev_b32_e32 v40, 16, v231
	v_add_f32_e32 v0, 1.0, v0
	v_rcp_f32_e32 v0, v0
	v_and_b32_e32 v53, 0xffff0000, v227
	v_and_b32_e32 v41, 0xffff0000, v231
	global_load_dwordx4 v[224:227], v[232:233], off
	global_load_dwordx4 v[228:231], v[234:235], off
	v_lshl_add_u64 v[232:233], v[232:233], 0, s[22:23]
	v_lshl_add_u64 v[234:235], v[234:235], 0, s[22:23]
	v_mul_f32_e32 v0, v143, v0
	v_mul_f32_e32 v0, v142, v0
	v_mov_b32_e32 v142, v63
	v_mov_b32_e32 v143, v47
	v_pk_fma_f32 v[138:139], v[22:23], v[142:143], v[138:139]
	s_nop 0
	v_mul_f32_e32 v142, 0x3d372713, v139
	v_mul_f32_e32 v142, v139, v142
	v_fma_f32 v142, v139, v142, v139
	v_mul_f32_e32 v142, 0x3f4c422a, v142
	v_mul_f32_e32 v142, -2.0, v142
	v_mul_f32_e32 v142, 0x3fb8aa3b, v142
	v_exp_f32_e32 v142, v142
	s_nop 0
	v_add_f32_e32 v142, 1.0, v142
	v_rcp_f32_e32 v142, v142
	s_nop 0
	v_mul_f32_e32 v139, v139, v142
	v_mul_f32_e32 v142, v138, v139
	v_mov_b32_e32 v138, v64
	v_mov_b32_e32 v139, v48
	v_pk_fma_f32 v[136:137], v[94:95], v[138:139], v[136:137]
	s_nop 0
	v_mul_f32_e32 v138, 0x3d372713, v137
	v_mul_f32_e32 v138, v137, v138
	v_fma_f32 v138, v137, v138, v137
	v_mul_f32_e32 v138, 0x3f4c422a, v138
	v_mul_f32_e32 v138, -2.0, v138
	v_mul_f32_e32 v138, 0x3fb8aa3b, v138
	v_exp_f32_e32 v138, v138
	s_nop 0
	v_add_f32_e32 v138, 1.0, v138
	v_rcp_f32_e32 v138, v138
	s_nop 0
	v_mul_f32_e32 v137, v137, v138
	v_mul_f32_e32 v138, v136, v137
	v_mov_b32_e32 v136, v65
	v_mov_b32_e32 v137, v49
	v_pk_fma_f32 v[134:135], v[24:25], v[136:137], v[134:135]
	s_nop 0
	v_mul_f32_e32 v136, 0x3d372713, v135
	v_mul_f32_e32 v136, v135, v136
	v_fma_f32 v136, v135, v136, v135
	v_mul_f32_e32 v136, 0x3f4c422a, v136
	v_mul_f32_e32 v136, -2.0, v136
	v_mul_f32_e32 v136, 0x3fb8aa3b, v136
	v_exp_f32_e32 v136, v136
	s_nop 0
	v_add_f32_e32 v136, 1.0, v136
	v_rcp_f32_e32 v136, v136
	s_nop 0
	v_mul_f32_e32 v135, v135, v136
	v_mul_f32_e32 v136, v134, v135
	v_mov_b32_e32 v134, v50
	v_mov_b32_e32 v135, v38
	v_pk_fma_f32 v[132:133], v[96:97], v[134:135], v[132:133]
	s_nop 0
	v_mul_f32_e32 v134, 0x3d372713, v133
	v_mul_f32_e32 v134, v133, v134
	v_fma_f32 v134, v133, v134, v133
	v_mul_f32_e32 v134, 0x3f4c422a, v134
	v_mul_f32_e32 v134, -2.0, v134
	v_mul_f32_e32 v134, 0x3fb8aa3b, v134
	v_exp_f32_e32 v134, v134
	s_nop 0
	v_add_f32_e32 v134, 1.0, v134
	v_rcp_f32_e32 v134, v134
	s_nop 0
	v_mul_f32_e32 v133, v133, v134
	v_mul_f32_e32 v134, v132, v133
	v_mov_b32_e32 v132, v51
	v_mov_b32_e32 v133, v39
	v_pk_fma_f32 v[130:131], v[18:19], v[132:133], v[130:131]
	s_nop 0
	v_mul_f32_e32 v132, 0x3d372713, v131
	v_mul_f32_e32 v132, v131, v132
	v_fma_f32 v132, v131, v132, v131
	v_mul_f32_e32 v132, 0x3f4c422a, v132
	v_mul_f32_e32 v132, -2.0, v132
	v_mul_f32_e32 v132, 0x3fb8aa3b, v132
	v_exp_f32_e32 v132, v132
	s_nop 0
	v_add_f32_e32 v132, 1.0, v132
	v_rcp_f32_e32 v132, v132
	s_nop 0
	v_mul_f32_e32 v131, v131, v132
	v_mul_f32_e32 v132, v130, v131
	v_mov_b32_e32 v130, v52
	v_mov_b32_e32 v131, v40
	v_pk_fma_f32 v[80:81], v[78:79], v[130:131], v[80:81]
	v_cvt_pk_bf16_f32 v131, v138, v136
	v_cvt_pk_bf16_f32 v132, v134, v132
	s_nop 0
	v_mul_f32_e32 v130, 0x3d372713, v81
	v_mul_f32_e32 v130, v81, v130
	v_fma_f32 v130, v81, v130, v81
	v_mul_f32_e32 v130, 0x3f4c422a, v130
	v_mul_f32_e32 v130, -2.0, v130
	v_mul_f32_e32 v130, 0x3fb8aa3b, v130
	v_exp_f32_e32 v130, v130
	s_nop 0
	v_add_f32_e32 v130, 1.0, v130
	v_rcp_f32_e32 v130, v130
	s_nop 0
	v_mul_f32_e32 v81, v81, v130
	v_mul_f32_e32 v133, v80, v81
	v_mov_b32_e32 v80, v53
	v_mov_b32_e32 v81, v41
	v_pk_fma_f32 v[76:77], v[20:21], v[80:81], v[76:77]
	v_cvt_pk_bf16_f32 v130, v0, v142
	s_nop 0
	v_mul_f32_e32 v80, 0x3d372713, v77
	v_mul_f32_e32 v80, v77, v80
	v_fma_f32 v80, v77, v80, v77
	v_mul_f32_e32 v80, 0x3f4c422a, v80
	v_mul_f32_e32 v80, -2.0, v80
	v_mul_f32_e32 v80, 0x3fb8aa3b, v80
	v_exp_f32_e32 v80, v80
	s_nop 0
	v_add_f32_e32 v80, 1.0, v80
	v_rcp_f32_e32 v80, v80
	s_nop 0
	v_mul_f32_e32 v77, v77, v80
	v_mul_f32_e32 v76, v76, v77
	v_cvt_pk_bf16_f32 v133, v133, v76
	v_mad_i64_i32 v[76:77], s[8:9], s13, v213, v[106:107]
	s_mov_b64 s[12:13], 0x16000
	v_lshl_add_u64 v[72:73], v[72:73], 0, s[12:13]
	global_store_dwordx4 v[76:77], v[130:133], off
	s_cbranch_scc1 .LBB0_561
	s_branch .LBB0_552
